# scan cross-term tiles staged through LDS and written with coalesced dwordx4 stores instead of scattered 8-byte stores
# speedup vs baseline: 1.0130x; 1.0130x over previous
; #define LAS __attribute__((address_space(3)))
; #define MFMA32(a, b, c) __builtin_amdgcn_mfma_f32_32x32x16_bf16((a), (b), (c), 0, 0, 0)
; template <bool XW, int PASS, bool RMW> ...
;     ...
;         const unsigned yb = yoff0 + (unsigned)c * 524288u;
;         f32x16 yc0, yc1;
; #pragma unroll
;         for (int i = 0; i < 16; ++i) { yc0[i] = 0.f; yc1[i] = 0.f; }
;         const LAS bf16_t* sp = Sb + pbuf * SBE + r * 264 + 8 * h;
; #pragma unroll
;         for (int sb = 0; sb < 8; ++sb) {
;           bf16x8 a0[2], a1[2];
; #pragma unroll
;           for (int k = 0; k < 2; ++k) { a0[k] = *(const LAS bf16x8*)(sp + 16 * (2 * sb + k)); a1[k] = *(const LAS bf16x8*)(sp + 32 * 264 + 16 * (2 * sb + k)); }
; #pragma unroll
;           for (int k = 0; k < 2; ++k) { yc0 = MFMA32(a0[k], qf[2 * sb + k], yc0); yc1 = MFMA32(a1[k], qf[2 * sb + k], yc1); }
;         }
;     ...
;       for (int i = 0; i < 16; ++i) { st0[i] *= cd; st1[i] *= cd; }
.LBB0_97:
	s_mul_i32 s8, s0, 0x8400
	v_add_u32_e32 v174, s8, v217
	ds_read_b128 v[232:235], v174
	ds_read_b128 v[236:239], v174 offset:16896
	ds_read_b128 v[240:243], v174 offset:32
	ds_read_b128 v[244:247], v174 offset:16928
	ds_read_b128 v[248:251], v174 offset:64
	s_add_i32 s8, s9, 1
	v_mov_b32_e32 v169, v168
	s_and_b32 s34, s1, 0x4000
	s_waitcnt vmcnt(29)
	s_waitcnt lgkmcnt(4)
	v_mfma_f32_32x32x16_bf16 v[48:63], v[232:235], v[128:131], 0
	ds_read_b128 v[232:235], v174 offset:16960
	s_min_u32 s35, s8, s5
	v_mul_f32_e64 v30, v168, v30
	v_mul_f32_e64 v31, v169, v31
	v_pk_mul_f32 v[28:29], v[168:169], v[28:29]
	v_pk_mul_f32 v[26:27], v[168:169], v[26:27]
	v_pk_mul_f32 v[24:25], v[168:169], v[24:25]
	v_pk_mul_f32 v[22:23], v[168:169], v[22:23]
	s_waitcnt lgkmcnt(4)
	v_mfma_f32_32x32x16_bf16 v[32:47], v[236:239], v[128:131], 0
	ds_read_b128 v[236:239], v174 offset:96
	ds_read_b128 v[128:131], v174 offset:16992
	v_mul_f32_e64 v20, v168, v20
	v_mul_f32_e64 v21, v169, v21
	v_mul_f32_e64 v18, v168, v18
	v_mul_f32_e64 v19, v169, v19
	v_mul_f32_e64 v14, v168, v14
	v_mul_f32_e64 v15, v169, v15
	v_pk_mul_f32 v[12:13], v[168:169], v[12:13]
	v_pk_mul_f32 v[10:11], v[168:169], v[10:11]
	v_pk_mul_f32 v[8:9], v[168:169], v[8:9]
	v_pk_mul_f32 v[6:7], v[168:169], v[6:7]
	s_waitcnt vmcnt(28)
	s_waitcnt lgkmcnt(5)
	v_mfma_f32_32x32x16_bf16 v[48:63], v[240:243], v[124:127], v[48:63]
	ds_read_b128 v[240:243], v174 offset:128
	v_mul_f32_e64 v4, v168, v4
	v_mul_f32_e64 v5, v169, v5
	v_mul_f32_e64 v2, v168, v2
	v_mul_f32_e64 v3, v169, v3
	v_add_u32_e32 v169, s34, v218
	s_lshl_b32 s34, s35, 18
	v_add_u32_e32 v175, 0xffffff90, v173
	v_pk_mul_f32 v[16:17], v[170:171], v[16:17]
	v_pk_mul_f32 v[0:1], v[170:171], v[0:1]
	s_waitcnt lgkmcnt(5)
	v_mfma_f32_32x32x16_bf16 v[32:47], v[244:247], v[124:127], v[32:47]
	ds_read_b128 v[244:247], v174 offset:17024
	ds_read_b128 v[124:127], v174 offset:160
	v_add_u32_e32 v184, -16, v173
	v_subrev_u32_e32 v185, 64, v173
	s_addk_i32 s1, 0x4000
	s_add_i32 s9, s9, 2
	s_and_b32 s35, s1, 0x4000
	s_min_u32 s9, s9, s5
	s_waitcnt vmcnt(27)
	s_waitcnt lgkmcnt(6)
	v_mfma_f32_32x32x16_bf16 v[48:63], v[248:251], v[120:123], v[48:63]
	ds_read_b128 v[248:251], v174 offset:17056
	s_xor_b32 s0, s0, 1
	s_cmp_lg_u32 s4, s8
	s_waitcnt lgkmcnt(6)
	v_mfma_f32_32x32x16_bf16 v[32:47], v[232:235], v[120:123], v[32:47]
	ds_read_b128 v[232:235], v174 offset:192
	ds_read_b128 v[120:123], v174 offset:17088
	s_waitcnt vmcnt(26)
	s_waitcnt lgkmcnt(7)
	v_mfma_f32_32x32x16_bf16 v[48:63], v[236:239], v[116:119], v[48:63]
	ds_read_b128 v[236:239], v174 offset:224
	s_waitcnt lgkmcnt(7)
	v_mfma_f32_32x32x16_bf16 v[32:47], v[128:131], v[116:119], v[32:47]
	ds_read_b128 v[128:131], v174 offset:17120
	v_subrev_u32_e32 v178, 48, v173
	v_add_u32_e32 v179, 0xffffffa0, v173
	v_subrev_u32_e32 v180, 32, v173
	v_add_u32_e32 v181, 0xffffffb0, v173
	s_waitcnt vmcnt(25)
	s_waitcnt lgkmcnt(7)
	v_mfma_f32_32x32x16_bf16 v[48:63], v[240:243], v[112:115], v[48:63]
	ds_read_b128 v[240:243], v174 offset:256
	s_waitcnt lgkmcnt(7)
	v_mfma_f32_32x32x16_bf16 v[32:47], v[244:247], v[112:115], v[32:47]
	ds_read_b128 v[244:247], v174 offset:17152
	s_waitcnt vmcnt(24)
	s_waitcnt lgkmcnt(7)
	v_mfma_f32_32x32x16_bf16 v[48:63], v[124:127], v[108:111], v[48:63]
	ds_read_b128 v[124:127], v174 offset:288
	s_waitcnt lgkmcnt(7)
	v_mfma_f32_32x32x16_bf16 v[32:47], v[248:251], v[108:111], v[32:47]
	ds_read_b128 v[248:251], v174 offset:17184
	s_waitcnt vmcnt(23)
	s_waitcnt lgkmcnt(7)
	v_mfma_f32_32x32x16_bf16 v[48:63], v[232:235], v[104:107], v[48:63]
	ds_read_b128 v[232:235], v174 offset:320
	s_waitcnt lgkmcnt(7)
	v_mfma_f32_32x32x16_bf16 v[32:47], v[120:123], v[104:107], v[32:47]
	ds_read_b128 v[120:123], v174 offset:17216
	s_waitcnt vmcnt(22)
	s_waitcnt lgkmcnt(7)
	v_mfma_f32_32x32x16_bf16 v[48:63], v[236:239], v[100:103], v[48:63]
	ds_read_b128 v[236:239], v174 offset:352
	s_waitcnt lgkmcnt(7)
	v_mfma_f32_32x32x16_bf16 v[32:47], v[128:131], v[100:103], v[32:47]
	ds_read_b128 v[128:131], v174 offset:17248
	s_waitcnt vmcnt(21)
	s_waitcnt lgkmcnt(7)
	v_mfma_f32_32x32x16_bf16 v[48:63], v[240:243], v[96:99], v[48:63]
	ds_read_b128 v[240:243], v174 offset:384
	s_waitcnt lgkmcnt(7)
	v_mfma_f32_32x32x16_bf16 v[32:47], v[244:247], v[96:99], v[32:47]
	ds_read_b128 v[244:247], v174 offset:17280
	s_waitcnt vmcnt(20)
	s_waitcnt lgkmcnt(7)
	v_mfma_f32_32x32x16_bf16 v[48:63], v[124:127], v[92:95], v[48:63]
	ds_read_b128 v[124:127], v174 offset:416
	s_waitcnt lgkmcnt(7)
	v_mfma_f32_32x32x16_bf16 v[32:47], v[248:251], v[92:95], v[32:47]
	ds_read_b128 v[248:251], v174 offset:17312
	s_waitcnt vmcnt(19)
	s_waitcnt lgkmcnt(7)
	v_mfma_f32_32x32x16_bf16 v[48:63], v[232:235], v[88:91], v[48:63]
	ds_read_b128 v[232:235], v174 offset:448
	s_waitcnt lgkmcnt(7)
	v_mfma_f32_32x32x16_bf16 v[32:47], v[120:123], v[88:91], v[32:47]
	ds_read_b128 v[120:123], v174 offset:17344
	s_waitcnt vmcnt(18)
	s_waitcnt lgkmcnt(7)
	v_mfma_f32_32x32x16_bf16 v[48:63], v[236:239], v[80:83], v[48:63]
	ds_read_b128 v[236:239], v174 offset:480
	s_waitcnt lgkmcnt(7)
	v_mfma_f32_32x32x16_bf16 v[32:47], v[128:131], v[80:83], v[32:47]
	ds_read_b128 v[128:131], v174 offset:17376
	s_waitcnt vmcnt(17)
	s_waitcnt lgkmcnt(7)
	v_mfma_f32_32x32x16_bf16 v[48:63], v[240:243], v[76:79], v[48:63]
	s_waitcnt lgkmcnt(6)
	v_mfma_f32_32x32x16_bf16 v[32:47], v[244:247], v[76:79], v[32:47]
	s_waitcnt vmcnt(16)
	s_waitcnt lgkmcnt(5)
	v_mfma_f32_32x32x16_bf16 v[48:63], v[124:127], v[72:75], v[48:63]
	v_add_u32_e32 v88, s34, v226
	v_or_b32_e32 v89, 0x400, v88
	v_or_b32_e32 v186, 0x3800, v88
	v_or_b32_e32 v187, 0x3c00, v88
	s_waitcnt lgkmcnt(4)
; #define LAS __attribute__((address_space(3)))
; DI unsigned cvt_pk_bf16(float lo, float hi) { unsigned r; asm volatile("v_cvt_pk_bf16_f32 %0, %1, %2" : "=v"(r) : "v"(lo), "v"(hi)); return r; }
; DI float bf_lo(unsigned w) { return __uint_as_float(w << 16); }
; DI float bf_hi(unsigned w) { return __uint_as_float(w & 0xffff0000u); }
; #define MFMA32(a, b, c) __builtin_amdgcn_mfma_f32_32x32x16_bf16((a), (b), (c), 0, 0, 0)
; template <bool XW, int PASS, bool RMW> ...
;     ...
;         asm volatile("" : "+v"(yc0), "+v"(yc1) :: "memory");
; #pragma unroll
;         for (int s = 0; s < 16; ++s) qf[s] = ldg16(qr, qoff0 + (unsigned)cn * 262144u + 1024u * s);
;         const float qe = cc > 0 ? qd : 0.f;
; #pragma unroll
;         for (int gq = 0; gq < 4; ++gq) {
;           u32x2 a; a.x = cvt_pk_bf16(bf_lo(ovn[gq].x) + qe * yc0[4 * gq], bf_hi(ovn[gq].x) + qe * yc0[4 * gq + 1]); a.y = cvt_pk_bf16(bf_lo(ovn[gq].y) + qe * yc0[4 * gq + 2], bf_hi(ovn[gq].y) + qe * yc0[4 * gq + 3]);
;           *(u32x2*)((char*)y + (yb + 16u * gq)) = a;
;           u32x2 c2; c2.x = cvt_pk_bf16(bf_lo(ovn[4 + gq].x) + qe * yc1[4 * gq], bf_hi(ovn[4 + gq].x) + qe * yc1[4 * gq + 1]); c2.y = cvt_pk_bf16(bf_lo(ovn[4 + gq].y) + qe * yc1[4 * gq + 2], bf_hi(ovn[4 + gq].y) + qe * yc1[4 * gq + 3]);
;           *(u32x2*)((char*)y + (yb + 64u + 16u * gq)) = c2;
;         }
;     ...
;       for (int sb = 0; sb < 2; ++sb) {
;         bf16x8 a0[4], a1[4];
; #pragma unroll
;         for (int k = 0; k < 4; ++k) { a0[k] = *(const LAS bf16x8*)(vimg + (cc & 1) * 16384 + (4 * sb + k) * 1024 + lane * 16); a1[k] = *(const LAS bf16x8*)(vimg + (cc & 1) * 16384 + 8192 + (4 * sb + k) * 1024 + lane * 16); }
; #pragma unroll
;         for (int k = 0; k < 4; ++k) { st0 = MFMA32(a0[k], kb0[4 * sb + k], st0); st1 = MFMA32(a1[k], kb0[4 * sb + k], st1); }
	v_mfma_f32_32x32x16_bf16 v[32:47], v[248:251], v[72:75], v[32:47]
	s_waitcnt vmcnt(15)
	s_waitcnt lgkmcnt(3)
	v_mfma_f32_32x32x16_bf16 v[48:63], v[232:235], v[68:71], v[48:63]
	v_or_b32_e32 v174, 0x3400, v88
	s_waitcnt lgkmcnt(2)
	v_mfma_f32_32x32x16_bf16 v[32:47], v[120:123], v[68:71], v[32:47]
	v_or_b32_e32 v68, 0x800, v88
	v_or_b32_e32 v69, 0xc00, v88
	v_or_b32_e32 v70, 0x1000, v88
	v_or_b32_e32 v71, 0x1400, v88
	v_or_b32_e32 v72, 0x1800, v88
	v_or_b32_e32 v73, 0x1c00, v88
	v_or_b32_e32 v74, 0x2000, v88
	s_waitcnt vmcnt(14)
	s_waitcnt lgkmcnt(1)
	v_mfma_f32_32x32x16_bf16 v[48:63], v[236:239], v[64:67], v[48:63]
	v_or_b32_e32 v75, 0x2400, v88
	v_or_b32_e32 v76, 0x2800, v88
	v_or_b32_e32 v77, 0x2c00, v88
	v_or_b32_e32 v78, 0x3000, v88
	s_waitcnt lgkmcnt(0)
	v_mfma_f32_32x32x16_bf16 v[32:47], v[128:131], v[64:67], v[32:47]
	global_load_dwordx4 v[128:131], v88, s[92:93]
	global_load_dwordx4 v[124:127], v89, s[92:93]
	global_load_dwordx4 v[120:123], v68, s[92:93]
	global_load_dwordx4 v[116:119], v69, s[92:93]
	global_load_dwordx4 v[112:115], v70, s[92:93]
	global_load_dwordx4 v[108:111], v71, s[92:93]
	global_load_dwordx4 v[104:107], v72, s[92:93]
	global_load_dwordx4 v[100:103], v73, s[92:93]
	global_load_dwordx4 v[96:99], v74, s[92:93]
	global_load_dwordx4 v[92:95], v75, s[92:93]
	global_load_dwordx4 v[88:91], v76, s[92:93]
	global_load_dwordx4 v[80:83], v77, s[92:93]
	s_nop 0
	global_load_dwordx4 v[76:79], v78, s[92:93]
	s_nop 0
	global_load_dwordx4 v[72:75], v174, s[92:93]
	global_load_dwordx4 v[68:71], v186, s[92:93]
	global_load_dwordx4 v[64:67], v187, s[92:93]
	v_mbcnt_lo_u32_b32 v211, -1, 0
	v_mbcnt_hi_u32_b32 v211, -1, v211
	v_readlane_b32 s100, v255, 12
	v_and_b32_e32 v240, 31, v211
	v_lshrrev_b32_e32 v241, 5, v211
	v_lshrrev_b32_e32 v242, 3, v211
	v_and_b32_e32 v243, 7, v211
	v_mov_b32_e32 v245, s100
	v_mul_u32_u24_e32 v245, 0x44, v245
	v_add_u32_e32 v245, 0x1a000, v245
	v_mul_u32_u24_e32 v204, 0x88, v240
	v_lshl_add_u32 v204, v241, 3, v204
	v_add_u32_e32 v204, v245, v204
	v_mul_u32_u24_e32 v205, 0x88, v242
	v_lshl_add_u32 v205, v243, 4, v205
	v_add_u32_e32 v205, v245, v205
	v_sub_u32_e32 v244, v242, v240
	v_lshlrev_b32_e32 v244, 12, v244
	v_lshl_add_u32 v244, v243, 4, v244
	v_lshlrev_b32_e32 v241, 3, v241
	v_sub_u32_e32 v244, v244, v241
	v_add_u32_e32 v207, v173, v244
	v_add_u32_e32 v207, 0xffffff90, v207
	v_add_u32_e32 v208, 0x8000, v207
	v_add_u32_e32 v209, 0x10000, v207
	v_add_u32_e32 v210, 0x18000, v207
	v_fma_f32 v48, v172, v48, 0
	v_fma_f32 v49, v172, v49, 0
	v_fma_f32 v50, v172, v50, 0
	v_fma_f32 v51, v172, v51, 0
	v_fma_f32 v52, v172, v52, 0
	v_fma_f32 v53, v172, v53, 0
	v_fma_f32 v54, v172, v54, 0
	v_fma_f32 v55, v172, v55, 0
	v_fma_f32 v56, v172, v56, 0
	v_fma_f32 v57, v172, v57, 0
	v_fma_f32 v58, v172, v58, 0
	v_fma_f32 v59, v172, v59, 0
	v_fma_f32 v60, v172, v60, 0
	v_fma_f32 v61, v172, v61, 0
	v_fma_f32 v62, v172, v62, 0
	v_fma_f32 v63, v172, v63, 0
	v_fma_f32 v32, v172, v32, 0
	v_fma_f32 v33, v172, v33, 0
	v_fma_f32 v34, v172, v34, 0
	v_fma_f32 v35, v172, v35, 0
	v_fma_f32 v36, v172, v36, 0
	v_fma_f32 v37, v172, v37, 0
	v_fma_f32 v38, v172, v38, 0
	v_fma_f32 v39, v172, v39, 0
	v_fma_f32 v40, v172, v40, 0
	v_fma_f32 v41, v172, v41, 0
	v_fma_f32 v42, v172, v42, 0
	v_fma_f32 v43, v172, v43, 0
	v_fma_f32 v44, v172, v44, 0
	v_fma_f32 v45, v172, v45, 0
	v_fma_f32 v46, v172, v46, 0
	v_fma_f32 v47, v172, v47, 0
	v_cvt_pk_bf16_f32 v232, v48, v49
	v_cvt_pk_bf16_f32 v233, v50, v51
	v_cvt_pk_bf16_f32 v234, v52, v53
	v_cvt_pk_bf16_f32 v235, v54, v55
	v_cvt_pk_bf16_f32 v236, v56, v57
	v_cvt_pk_bf16_f32 v237, v58, v59
	v_cvt_pk_bf16_f32 v238, v60, v61
	v_cvt_pk_bf16_f32 v239, v62, v63
	v_cvt_pk_bf16_f32 v240, v32, v33
	v_cvt_pk_bf16_f32 v241, v34, v35
	v_cvt_pk_bf16_f32 v242, v36, v37
	v_cvt_pk_bf16_f32 v243, v38, v39
	v_cvt_pk_bf16_f32 v244, v40, v41
	v_cvt_pk_bf16_f32 v245, v42, v43
	v_cvt_pk_bf16_f32 v246, v44, v45
	v_cvt_pk_bf16_f32 v247, v46, v47
	ds_write_b64 v204, v[232:233]
	ds_write_b64 v204, v[234:235] offset:16
	ds_write_b64 v204, v[236:237] offset:32
	ds_write_b64 v204, v[238:239] offset:48
	ds_write_b64 v204, v[240:241] offset:64
	ds_write_b64 v204, v[242:243] offset:80
	ds_write_b64 v204, v[244:245] offset:96
	ds_write_b64 v204, v[246:247] offset:112
	s_waitcnt lgkmcnt(0)
	ds_read_b128 v[232:235], v205
	ds_read_b128 v[236:239], v205 offset:1088
	ds_read_b128 v[240:243], v205 offset:2176
	ds_read_b128 v[244:247], v205 offset:3264
	s_waitcnt lgkmcnt(0)
	global_store_dwordx4 v207, v[232:235], s[18:19]
	global_store_dwordx4 v208, v[236:239], s[18:19]
	global_store_dwordx4 v209, v[240:243], s[18:19]
	global_store_dwordx4 v210, v[244:247], s[18:19]
	s_nop 1
	ds_read_b128 v[232:235], v169
	ds_read_b128 v[236:239], v169 offset:8192
	ds_read_b128 v[240:243], v169 offset:1024
	ds_read_b128 v[244:247], v169 offset:9216
	ds_read_b128 v[248:251], v169 offset:2048
	s_waitcnt vmcnt(29)
	s_waitcnt lgkmcnt(4)
	v_mfma_f32_32x32x16_bf16 v[16:31], v[232:235], v[164:167], v[16:31]
	ds_read_b128 v[232:235], v169 offset:10240
	v_add_u32_e32 v62, s34, v223
	s_waitcnt vmcnt(21)
	v_lshlrev_b32_e32 v46, 16, v152
	v_and_b32_e32 v47, 0xffff0000, v152
	v_lshlrev_b32_e32 v48, 16, v153
	v_and_b32_e32 v49, 0xffff0000, v153
	v_add_u32_e32 v60, s35, v198
	s_waitcnt lgkmcnt(4)
	v_mfma_f32_32x32x16_bf16 v[0:15], v[236:239], v[164:167], v[0:15]
	ds_read_b128 v[236:239], v169 offset:3072
	v_lshlrev_b32_e32 v50, 16, v154
	v_and_b32_e32 v51, 0xffff0000, v154
	v_lshlrev_b32_e32 v52, 16, v155
	v_lshl_add_u32 v61, s9, 19, v224
	v_add_u32_e32 v63, s3, v60
	s_waitcnt vmcnt(20)
	v_and_b32_e32 v53, 0xffff0000, v148
	v_lshlrev_b32_e32 v54, 16, v149
	s_waitcnt lgkmcnt(4)
; #define LAS __attribute__((address_space(3)))
; DI unsigned cvt_pk_bf16(float lo, float hi) { unsigned r; asm volatile("v_cvt_pk_bf16_f32 %0, %1, %2" : "=v"(r) : "v"(lo), "v"(hi)); return r; }
; #define MFMA32(a, b, c) __builtin_amdgcn_mfma_f32_32x32x16_bf16((a), (b), (c), 0, 0, 0)
; template <bool XW, int PASS, bool RMW> ...
;     ...
;       for (int sb = 0; sb < 2; ++sb) {
;         bf16x8 a0[4], a1[4];
; #pragma unroll
;         for (int k = 0; k < 4; ++k) { a0[k] = *(const LAS bf16x8*)(vimg + (cc & 1) * 16384 + (4 * sb + k) * 1024 + lane * 16); a1[k] = *(const LAS bf16x8*)(vimg + (cc & 1) * 16384 + 8192 + (4 * sb + k) * 1024 + lane * 16); }
; #pragma unroll
;         for (int k = 0; k < 4; ++k) { st0 = MFMA32(a0[k], kb0[4 * sb + k], st0); st1 = MFMA32(a1[k], kb0[4 * sb + k], st1); }
;         asm volatile("" : "+v"(st0), "+v"(st1) :: "memory");
; #pragma unroll
;         for (int k = 0; k < 4; ++k) kb0[4 * sb + k] = ldg16(kT, kboff0 + (unsigned)cn * 262144u + 1024u * (4 * sb + k));
;       }
; #pragma unroll
;       for (int t = 0; t < 2; ++t) {
;         const int sv = 2 * dq + t;
;         *(LAS bf16x8*)(vimg + ((cc + 1) & 1) * 16384 + et * 8192 + sv * 1024 + lane * 16) = scale_tab(vr[t], kdec + 16 * sv + 8 * h);
;         vr[t] = ldg16(vT, vaoff0 + (unsigned)cnn * 524288u + 1024u * sv);
;       }
;       LAS bf16_t* sw = Sb + (pbuf ^ 1) * SBE + (4 * h) * 264 + 32 * w + r;
; #pragma unroll
;       for (int i = 0; i < 16; ++i) {
;         const int eo = ((i & 3) + 8 * (i >> 2)) * 264;
;         const unsigned pkw = cvt_pk_bf16(st0[i], st1[i]);
;         sw[eo] = (bf16_t)(pkw & 0xffffu);
;         sw[eo + 32 * 264] = (bf16_t)(pkw >> 16);
;       }
;       lds_barrier();
;       pbuf ^= 1;
	v_mfma_f32_32x32x16_bf16 v[16:31], v[240:243], v[160:163], v[16:31]
	ds_read_b128 v[240:243], v169 offset:11264
	v_and_b32_e32 v55, 0xffff0000, v149
	v_lshlrev_b32_e32 v56, 16, v150
	v_and_b32_e32 v57, 0xffff0000, v150
	v_lshlrev_b32_e32 v58, 16, v151
	v_and_b32_e32 v59, 0xffff0000, v151
	s_mul_i32 s9, s0, 0x8400
	s_waitcnt lgkmcnt(4)
	v_mfma_f32_32x32x16_bf16 v[0:15], v[244:247], v[160:163], v[0:15]
	ds_read_b128 v[244:247], v169 offset:4096
	s_waitcnt lgkmcnt(4)
	v_mfma_f32_32x32x16_bf16 v[16:31], v[248:251], v[156:159], v[16:31]
	ds_read_b128 v[248:251], v169 offset:12288
	v_and_b32_e32 v44, 0xffff0000, v155
	v_lshlrev_b32_e32 v45, 16, v148
	v_or_b32_e32 v148, s3, v61
	v_or_b32_e32 v61, s33, v61
	v_add_u32_e32 v173, 0x80000, v173
	s_waitcnt lgkmcnt(4)
	v_mfma_f32_32x32x16_bf16 v[0:15], v[232:235], v[156:159], v[0:15]
	ds_read_b128 v[232:235], v169 offset:5120
	s_waitcnt lgkmcnt(4)
	v_mfma_f32_32x32x16_bf16 v[16:31], v[236:239], v[140:143], v[16:31]
	ds_read_b128 v[236:239], v169 offset:13312
	s_waitcnt lgkmcnt(4)
	v_mfma_f32_32x32x16_bf16 v[0:15], v[240:243], v[140:143], v[0:15]
	ds_read_b128 v[240:243], v169 offset:6144
	s_waitcnt lgkmcnt(4)
	v_mfma_f32_32x32x16_bf16 v[16:31], v[244:247], v[144:147], v[16:31]
	ds_read_b128 v[244:247], v169 offset:14336
	s_waitcnt lgkmcnt(4)
	v_mfma_f32_32x32x16_bf16 v[0:15], v[248:251], v[144:147], v[0:15]
	ds_read_b128 v[248:251], v169 offset:7168
	s_waitcnt lgkmcnt(4)
	v_mfma_f32_32x32x16_bf16 v[16:31], v[232:235], v[136:139], v[16:31]
	ds_read_b128 v[232:235], v169 offset:15360
	s_waitcnt lgkmcnt(4)
	v_mfma_f32_32x32x16_bf16 v[0:15], v[236:239], v[136:139], v[0:15]
	s_waitcnt lgkmcnt(3)
	v_mfma_f32_32x32x16_bf16 v[16:31], v[240:243], v[132:135], v[16:31]
	s_waitcnt lgkmcnt(2)
	v_mfma_f32_32x32x16_bf16 v[0:15], v[244:247], v[132:135], v[0:15]
	v_or_b32_e32 v32, 0x400, v62
	v_or_b32_e32 v33, 0x800, v62
	v_or_b32_e32 v34, 0xc00, v62
	global_load_dwordx4 v[164:167], v62, s[14:15]
	global_load_dwordx4 v[160:163], v32, s[14:15]
	global_load_dwordx4 v[156:159], v33, s[14:15]
	global_load_dwordx4 v[140:143], v34, s[14:15]
	v_or_b32_e32 v132, 0x1000, v62
	s_waitcnt lgkmcnt(1)
	v_mfma_f32_32x32x16_bf16 v[16:31], v[248:251], v[84:87], v[16:31]
	v_or_b32_e32 v36, 0x1400, v62
	v_or_b32_e32 v37, 0x1800, v62
	v_or_b32_e32 v38, 0x1c00, v62
	s_waitcnt lgkmcnt(0)
	v_mfma_f32_32x32x16_bf16 v[0:15], v[232:235], v[84:87], v[0:15]
	ds_read_b128 v[32:35], v228
	global_load_dwordx4 v[144:147], v132, s[14:15]
	global_load_dwordx4 v[136:139], v36, s[14:15]
	s_nop 0
	global_load_dwordx4 v[132:135], v37, s[14:15]
	global_load_dwordx4 v[84:87], v38, s[14:15]
	ds_read_b128 v[36:39], v228 offset:16
	s_waitcnt lgkmcnt(1)
	v_mul_f32_e32 v32, v32, v46
	v_mul_f32_e32 v33, v33, v47
	v_mul_f32_e32 v34, v34, v48
	v_mul_f32_e32 v35, v35, v49
	s_waitcnt lgkmcnt(0)
	v_mul_f32_e32 v36, v36, v50
	v_mul_f32_e32 v37, v37, v51
	v_mul_f32_e32 v38, v38, v52
	v_mul_f32_e32 v39, v39, v44
	v_cvt_pk_bf16_f32 v32, v32, v33
	v_cvt_pk_bf16_f32 v33, v34, v35
	v_cvt_pk_bf16_f32 v34, v36, v37
	v_cvt_pk_bf16_f32 v35, v38, v39
	ds_write_b128 v63, v[32:35]
	global_load_dwordx4 v[152:155], v148, s[16:17]
	ds_read_b128 v[32:35], v229
	ds_read_b128 v[36:39], v229 offset:16
	s_waitcnt lgkmcnt(1)
	v_mul_f32_e32 v32, v32, v45
	v_mul_f32_e32 v33, v33, v53
	v_mul_f32_e32 v34, v34, v54
	v_mul_f32_e32 v35, v35, v55
	s_waitcnt lgkmcnt(0)
	v_mul_f32_e32 v36, v36, v56
	v_mul_f32_e32 v37, v37, v57
	v_mul_f32_e32 v38, v38, v58
	v_mul_f32_e32 v39, v39, v59
	v_cvt_pk_bf16_f32 v32, v32, v33
	v_cvt_pk_bf16_f32 v33, v34, v35
	v_cvt_pk_bf16_f32 v34, v36, v37
	v_cvt_pk_bf16_f32 v35, v38, v39
	global_load_dwordx4 v[148:151], v61, s[16:17]
	v_add_u32_e32 v37, s33, v60
	v_add_u32_e32 v36, s9, v199
	ds_write_b128 v37, v[32:35]
	v_mbcnt_lo_u32_b32 v251, -1, 0
	v_mbcnt_hi_u32_b32 v251, -1, v251
	v_and_b32_e32 v251, 1, v251
	v_sub_u32_e32 v250, 0, v251
	v_and_b32_e32 v248, 0x06060606, v250
	v_xor_b32_e32 v248, 0x05040100, v248
	v_and_b32_e32 v251, 0x107e, v250
	v_add_u32_e32 v249, v36, v251
	v_cvt_pk_bf16_f32 v232, v16, v20
	v_cvt_pk_bf16_f32 v233, v17, v21
	v_cvt_pk_bf16_f32 v234, v18, v22
	v_cvt_pk_bf16_f32 v235, v19, v23
	v_cvt_pk_bf16_f32 v236, v24, v28
	v_cvt_pk_bf16_f32 v237, v25, v29
	v_cvt_pk_bf16_f32 v238, v26, v30
	v_cvt_pk_bf16_f32 v239, v27, v31
	v_mov_b32_dpp v240, v232 quad_perm:[1,0,3,2] row_mask:0xf bank_mask:0xf
	v_mov_b32_dpp v241, v233 quad_perm:[1,0,3,2] row_mask:0xf bank_mask:0xf
	v_mov_b32_dpp v242, v234 quad_perm:[1,0,3,2] row_mask:0xf bank_mask:0xf
	v_mov_b32_dpp v243, v235 quad_perm:[1,0,3,2] row_mask:0xf bank_mask:0xf
	v_mov_b32_dpp v244, v236 quad_perm:[1,0,3,2] row_mask:0xf bank_mask:0xf
	v_mov_b32_dpp v245, v237 quad_perm:[1,0,3,2] row_mask:0xf bank_mask:0xf
	v_mov_b32_dpp v246, v238 quad_perm:[1,0,3,2] row_mask:0xf bank_mask:0xf
	v_mov_b32_dpp v247, v239 quad_perm:[1,0,3,2] row_mask:0xf bank_mask:0xf
	v_perm_b32 v240, v240, v232, v248
	v_perm_b32 v241, v241, v233, v248
	v_perm_b32 v242, v242, v234, v248
	v_perm_b32 v243, v243, v235, v248
	v_perm_b32 v244, v244, v236, v248
	v_perm_b32 v245, v245, v237, v248
	v_perm_b32 v246, v246, v238, v248
	v_perm_b32 v247, v247, v239, v248
	ds_write_b32 v249, v240 offset:0
	ds_write_b32 v249, v241 offset:528
	ds_write_b32 v249, v242 offset:1056
	ds_write_b32 v249, v243 offset:1584
	ds_write_b32 v249, v244 offset:8448
	ds_write_b32 v249, v245 offset:8976
	ds_write_b32 v249, v246 offset:9504
	ds_write_b32 v249, v247 offset:10032
	v_cvt_pk_bf16_f32 v232, v0, v4
	v_cvt_pk_bf16_f32 v233, v1, v5
	v_cvt_pk_bf16_f32 v234, v2, v6
	v_cvt_pk_bf16_f32 v235, v3, v7
	v_cvt_pk_bf16_f32 v236, v8, v12
	v_cvt_pk_bf16_f32 v237, v9, v13
	v_cvt_pk_bf16_f32 v238, v10, v14
	v_cvt_pk_bf16_f32 v239, v11, v15
	v_mov_b32_dpp v240, v232 quad_perm:[1,0,3,2] row_mask:0xf bank_mask:0xf
	v_mov_b32_dpp v241, v233 quad_perm:[1,0,3,2] row_mask:0xf bank_mask:0xf
	v_mov_b32_dpp v242, v234 quad_perm:[1,0,3,2] row_mask:0xf bank_mask:0xf
	v_mov_b32_dpp v243, v235 quad_perm:[1,0,3,2] row_mask:0xf bank_mask:0xf
	v_mov_b32_dpp v244, v236 quad_perm:[1,0,3,2] row_mask:0xf bank_mask:0xf
	v_mov_b32_dpp v245, v237 quad_perm:[1,0,3,2] row_mask:0xf bank_mask:0xf
	v_mov_b32_dpp v246, v238 quad_perm:[1,0,3,2] row_mask:0xf bank_mask:0xf
	v_mov_b32_dpp v247, v239 quad_perm:[1,0,3,2] row_mask:0xf bank_mask:0xf
	v_perm_b32 v240, v240, v232, v248
	v_perm_b32 v241, v241, v233, v248
	v_perm_b32 v242, v242, v234, v248
	v_perm_b32 v243, v243, v235, v248
	v_perm_b32 v244, v244, v236, v248
	v_perm_b32 v245, v245, v237, v248
	v_perm_b32 v246, v246, v238, v248
	v_perm_b32 v247, v247, v239, v248
	ds_write_b32 v249, v240 offset:16896
	ds_write_b32 v249, v241 offset:17424
	ds_write_b32 v249, v242 offset:17952
	ds_write_b32 v249, v243 offset:18480
	ds_write_b32 v249, v244 offset:25344
	ds_write_b32 v249, v245 offset:25872
	ds_write_b32 v249, v246 offset:26400
	ds_write_b32 v249, v247 offset:26928
	s_waitcnt lgkmcnt(0)
	s_barrier
; #define EX2(x) __builtin_amdgcn_exp2f(x)
; template <bool XW, int PASS, bool RMW> ...
;     ...
;     if (tids < 128) kdec[tids] = EX2(lg * (float)(PASS == 0 ? 127 - tids : tids));
; template <bool XW> ...
;   if (mode != 2) scan_pass<XW, 0, true>(qr, kT, vT, y, Sb, kdec, vimg, tids, lane, r, h, w, et, dq, icol, nc, qoff0, vaoff0, kboff0, yoff0, lgf, lgb);
;   if (mode == 0) scan_pass<XW, 1, true>(qr, kT, vT, y, Sb, kdec, vimg, tids, lane, r, h, w, et, dq, icol, nc, qoff0, vaoff0, kboff0, yoff0, lgf, lgb);
;   if (mode == 2) scan_pass<XW, 1, false>(qr, kT, vT, yb, Sb, kdec, vimg, tids, lane, r, h, w, et, dq, icol, nc, qoff0, vaoff0, kboff0, yoff0, lgf, lgb);
	s_mov_b32 s9, s8
	s_cbranch_scc1 .LBB0_97
	s_cmp_lg_u32 s31, 0
	s_cbranch_scc1 .LBB0_103
	s_and_saveexec_b64 s[0:1], s[6:7]
	s_cbranch_execz .LBB0_101
	v_mul_f32_e64 v0, v200, -v225
	v_exp_f32_e32 v0, v0
	ds_write_b32 v195, v0

; #define LAS __attribute__((address_space(3)))
; #define MFMA32(a, b, c) __builtin_amdgcn_mfma_f32_32x32x16_bf16((a), (b), (c), 0, 0, 0)
; template <bool XW, int PASS, bool RMW> ...
;     ...
;         const unsigned yb = yoff0 + (unsigned)c * 524288u;
;         f32x16 yc0, yc1;
; #pragma unroll
;         for (int i = 0; i < 16; ++i) { yc0[i] = 0.f; yc1[i] = 0.f; }
;         const LAS bf16_t* sp = Sb + pbuf * SBE + r * 264 + 8 * h;
; #pragma unroll
;         for (int sb = 0; sb < 8; ++sb) {
;           bf16x8 a0[2], a1[2];
; #pragma unroll
;           for (int k = 0; k < 2; ++k) { a0[k] = *(const LAS bf16x8*)(sp + 16 * (2 * sb + k)); a1[k] = *(const LAS bf16x8*)(sp + 32 * 264 + 16 * (2 * sb + k)); }
; #pragma unroll
;           for (int k = 0; k < 2; ++k) { yc0 = MFMA32(a0[k], qf[2 * sb + k], yc0); yc1 = MFMA32(a1[k], qf[2 * sb + k], yc1); }
;         }
;     ...
;       for (int i = 0; i < 16; ++i) { st0[i] *= cd; st1[i] *= cd; }
.LBB0_108:
	s_mul_i32 s2, s0, 0x8400
	v_add_u32_e32 v186, s2, v217
	ds_read_b128 v[228:231], v186
	ds_read_b128 v[232:235], v186 offset:16896
	ds_read_b128 v[236:239], v186 offset:32
	ds_read_b128 v[240:243], v186 offset:16928
	ds_read_b128 v[244:247], v186 offset:64
	ds_read_b128 v[248:251], v186 offset:16960
	s_add_i32 s2, s8, 1
	v_mov_b32_e32 v169, v168
	s_and_b32 s9, s1, 0x4000
	s_waitcnt vmcnt(29)
	s_waitcnt lgkmcnt(5)
	v_mfma_f32_32x32x16_bf16 v[48:63], v[228:231], v[124:127], 0
	ds_read_b128 v[228:231], v186 offset:96
	v_mul_f32_e64 v30, v168, v30
	v_mul_f32_e64 v31, v169, v31
	v_mul_f32_e64 v28, v168, v28
	v_mul_f32_e64 v29, v169, v29
	v_pk_mul_f32 v[26:27], v[168:169], v[26:27]
	v_pk_mul_f32 v[24:25], v[168:169], v[24:25]
	v_pk_mul_f32 v[22:23], v[168:169], v[22:23]
	v_pk_mul_f32 v[20:21], v[168:169], v[20:21]
	s_waitcnt lgkmcnt(5)
	v_mfma_f32_32x32x16_bf16 v[32:47], v[232:235], v[124:127], 0
	ds_read_b128 v[232:235], v186 offset:16992
	ds_read_b128 v[124:127], v186 offset:128
	v_mul_f32_e64 v18, v168, v18
	v_mul_f32_e64 v19, v169, v19
	v_mul_f32_e64 v14, v168, v14
	v_mul_f32_e64 v15, v169, v15
	v_mul_f32_e64 v12, v168, v12
	v_mul_f32_e64 v13, v169, v13
	v_pk_mul_f32 v[10:11], v[168:169], v[10:11]
	v_pk_mul_f32 v[8:9], v[168:169], v[8:9]
	v_pk_mul_f32 v[6:7], v[168:169], v[6:7]
	v_pk_mul_f32 v[4:5], v[168:169], v[4:5]
	s_waitcnt vmcnt(28)
	s_waitcnt lgkmcnt(6)
	v_mfma_f32_32x32x16_bf16 v[48:63], v[236:239], v[120:123], v[48:63]
	ds_read_b128 v[236:239], v186 offset:17024
	v_mul_f32_e64 v2, v168, v2
	v_mul_f32_e64 v3, v169, v3
	v_add_u32_e32 v169, s9, v218
	v_mul_f32_e64 v16, v170, v16
	v_mul_f32_e64 v17, v171, v17
	v_pk_mul_f32 v[0:1], v[170:171], v[0:1]
	s_add_i32 s8, s8, 2
	s_addk_i32 s1, 0x4000
	s_xor_b32 s0, s0, 1
	s_waitcnt lgkmcnt(6)
	v_mfma_f32_32x32x16_bf16 v[32:47], v[240:243], v[120:123], v[32:47]
	ds_read_b128 v[240:243], v186 offset:160
	ds_read_b128 v[120:123], v186 offset:17056
	v_add_u32_e32 v182, 0x60, v175
	v_add_u32_e32 v183, 48, v175
	s_waitcnt vmcnt(27)
	s_waitcnt lgkmcnt(7)
	v_mfma_f32_32x32x16_bf16 v[48:63], v[244:247], v[116:119], v[48:63]
	ds_read_b128 v[244:247], v186 offset:192
	s_waitcnt lgkmcnt(7)
	v_mfma_f32_32x32x16_bf16 v[32:47], v[248:251], v[116:119], v[32:47]
	ds_read_b128 v[248:251], v186 offset:17088
	s_waitcnt vmcnt(26)
	s_waitcnt lgkmcnt(7)
	v_mfma_f32_32x32x16_bf16 v[48:63], v[228:231], v[112:115], v[48:63]
	ds_read_b128 v[228:231], v186 offset:224
	s_waitcnt lgkmcnt(7)
	v_mfma_f32_32x32x16_bf16 v[32:47], v[232:235], v[112:115], v[32:47]
	ds_read_b128 v[232:235], v186 offset:17120
	v_add_u32_e32 v178, 64, v175
	v_add_u32_e32 v179, 16, v175
	v_add_u32_e32 v180, 0x50, v175
	v_add_u32_e32 v181, 32, v175
	s_waitcnt vmcnt(25)
	s_waitcnt lgkmcnt(7)
	v_mfma_f32_32x32x16_bf16 v[48:63], v[124:127], v[108:111], v[48:63]
	ds_read_b128 v[124:127], v186 offset:256
	s_waitcnt lgkmcnt(7)
	v_mfma_f32_32x32x16_bf16 v[32:47], v[236:239], v[108:111], v[32:47]
	ds_read_b128 v[236:239], v186 offset:17152
	s_waitcnt vmcnt(24)
	s_waitcnt lgkmcnt(7)
	v_mfma_f32_32x32x16_bf16 v[48:63], v[240:243], v[104:107], v[48:63]
	ds_read_b128 v[240:243], v186 offset:288
	s_waitcnt lgkmcnt(7)
	v_mfma_f32_32x32x16_bf16 v[32:47], v[120:123], v[104:107], v[32:47]
	ds_read_b128 v[120:123], v186 offset:17184
	s_waitcnt vmcnt(23)
	s_waitcnt lgkmcnt(7)
	v_mfma_f32_32x32x16_bf16 v[48:63], v[244:247], v[100:103], v[48:63]
	ds_read_b128 v[244:247], v186 offset:320
	s_waitcnt lgkmcnt(7)
	v_mfma_f32_32x32x16_bf16 v[32:47], v[248:251], v[100:103], v[32:47]
	ds_read_b128 v[248:251], v186 offset:17216
	s_waitcnt vmcnt(22)
	s_waitcnt lgkmcnt(7)
	v_mfma_f32_32x32x16_bf16 v[48:63], v[228:231], v[96:99], v[48:63]
	ds_read_b128 v[228:231], v186 offset:352
	s_waitcnt lgkmcnt(7)
	v_mfma_f32_32x32x16_bf16 v[32:47], v[232:235], v[96:99], v[32:47]
	ds_read_b128 v[232:235], v186 offset:17248
	s_waitcnt vmcnt(21)
	s_waitcnt lgkmcnt(7)
	v_mfma_f32_32x32x16_bf16 v[48:63], v[124:127], v[92:95], v[48:63]
	ds_read_b128 v[124:127], v186 offset:384
	s_waitcnt lgkmcnt(7)
	v_mfma_f32_32x32x16_bf16 v[32:47], v[236:239], v[92:95], v[32:47]
	ds_read_b128 v[236:239], v186 offset:17280
	s_waitcnt vmcnt(20)
	s_waitcnt lgkmcnt(7)
	v_mfma_f32_32x32x16_bf16 v[48:63], v[240:243], v[88:91], v[48:63]
	ds_read_b128 v[240:243], v186 offset:416
	s_waitcnt lgkmcnt(7)
	v_mfma_f32_32x32x16_bf16 v[32:47], v[120:123], v[88:91], v[32:47]
	ds_read_b128 v[120:123], v186 offset:17312
	s_waitcnt vmcnt(19)
	s_waitcnt lgkmcnt(7)
	v_mfma_f32_32x32x16_bf16 v[48:63], v[244:247], v[84:87], v[48:63]
	ds_read_b128 v[244:247], v186 offset:448
	s_waitcnt lgkmcnt(7)
	v_mfma_f32_32x32x16_bf16 v[32:47], v[248:251], v[84:87], v[32:47]
	ds_read_b128 v[248:251], v186 offset:17344
	s_waitcnt vmcnt(18)
	s_waitcnt lgkmcnt(7)
	v_mfma_f32_32x32x16_bf16 v[48:63], v[228:231], v[80:83], v[48:63]
	ds_read_b128 v[228:231], v186 offset:480
	v_mov_b32_e32 v92, s2
	s_waitcnt lgkmcnt(7)
	v_mfma_f32_32x32x16_bf16 v[32:47], v[232:235], v[80:83], v[32:47]
	ds_read_b128 v[232:235], v186 offset:17376
	s_waitcnt vmcnt(17)
	s_waitcnt lgkmcnt(7)
	v_mfma_f32_32x32x16_bf16 v[48:63], v[124:127], v[76:79], v[48:63]
	s_waitcnt lgkmcnt(6)
	v_mfma_f32_32x32x16_bf16 v[32:47], v[236:239], v[76:79], v[32:47]
	s_waitcnt vmcnt(16)
	s_waitcnt lgkmcnt(5)
	v_mfma_f32_32x32x16_bf16 v[48:63], v[240:243], v[72:75], v[48:63]
	v_sub_u32_e64 v84, s5, v92 clamp
	v_lshlrev_b32_e32 v184, 18, v84
	v_add_u32_e32 v84, v184, v226
	v_or_b32_e32 v85, 0x400, v84
	v_or_b32_e32 v185, 0x3400, v84
	v_or_b32_e32 v187, 0x3c00, v84
	s_waitcnt lgkmcnt(4)
	v_mfma_f32_32x32x16_bf16 v[32:47], v[120:123], v[72:75], v[32:47]
	s_waitcnt vmcnt(15)
	s_waitcnt lgkmcnt(3)
; #define LAS __attribute__((address_space(3)))
; DI unsigned cvt_pk_bf16(float lo, float hi) { unsigned r; asm volatile("v_cvt_pk_bf16_f32 %0, %1, %2" : "=v"(r) : "v"(lo), "v"(hi)); return r; }
; DI float bf_lo(unsigned w) { return __uint_as_float(w << 16); }
; DI float bf_hi(unsigned w) { return __uint_as_float(w & 0xffff0000u); }
; #define MFMA32(a, b, c) __builtin_amdgcn_mfma_f32_32x32x16_bf16((a), (b), (c), 0, 0, 0)
; template <bool XW, int PASS, bool RMW> ...
;     ...
;         asm volatile("" : "+v"(yc0), "+v"(yc1) :: "memory");
; #pragma unroll
;         for (int s = 0; s < 16; ++s) qf[s] = ldg16(qr, qoff0 + (unsigned)cn * 262144u + 1024u * s);
;         const float qe = cc > 0 ? qd : 0.f;
; #pragma unroll
;         for (int gq = 0; gq < 4; ++gq) {
;           u32x2 a; a.x = cvt_pk_bf16(bf_lo(ovn[gq].x) + qe * yc0[4 * gq], bf_hi(ovn[gq].x) + qe * yc0[4 * gq + 1]); a.y = cvt_pk_bf16(bf_lo(ovn[gq].y) + qe * yc0[4 * gq + 2], bf_hi(ovn[gq].y) + qe * yc0[4 * gq + 3]);
;           *(u32x2*)((char*)y + (yb + 16u * gq)) = a;
;           u32x2 c2; c2.x = cvt_pk_bf16(bf_lo(ovn[4 + gq].x) + qe * yc1[4 * gq], bf_hi(ovn[4 + gq].x) + qe * yc1[4 * gq + 1]); c2.y = cvt_pk_bf16(bf_lo(ovn[4 + gq].y) + qe * yc1[4 * gq + 2], bf_hi(ovn[4 + gq].y) + qe * yc1[4 * gq + 3]);
;           *(u32x2*)((char*)y + (yb + 64u + 16u * gq)) = c2;
;         }
;     ...
;       for (int sb = 0; sb < 2; ++sb) {
;         bf16x8 a0[4], a1[4];
; #pragma unroll
;         for (int k = 0; k < 4; ++k) { a0[k] = *(const LAS bf16x8*)(vimg + (cc & 1) * 16384 + (4 * sb + k) * 1024 + lane * 16); a1[k] = *(const LAS bf16x8*)(vimg + (cc & 1) * 16384 + 8192 + (4 * sb + k) * 1024 + lane * 16); }
; #pragma unroll
;         for (int k = 0; k < 4; ++k) { st0 = MFMA32(a0[k], kb0[4 * sb + k], st0); st1 = MFMA32(a1[k], kb0[4 * sb + k], st1); }
	v_mfma_f32_32x32x16_bf16 v[48:63], v[244:247], v[68:71], v[48:63]
	v_or_b32_e32 v186, 0x3800, v84
	s_waitcnt lgkmcnt(2)
	v_mfma_f32_32x32x16_bf16 v[32:47], v[248:251], v[68:71], v[32:47]
	v_or_b32_e32 v68, 0x800, v84
	v_or_b32_e32 v69, 0xc00, v84
	v_or_b32_e32 v70, 0x1000, v84
	v_or_b32_e32 v71, 0x1400, v84
	v_or_b32_e32 v72, 0x1800, v84
	v_or_b32_e32 v73, 0x1c00, v84
	v_or_b32_e32 v74, 0x2000, v84
	s_waitcnt vmcnt(14)
	s_waitcnt lgkmcnt(1)
	v_mfma_f32_32x32x16_bf16 v[48:63], v[228:231], v[64:67], v[48:63]
	v_or_b32_e32 v75, 0x2400, v84
	v_or_b32_e32 v76, 0x2800, v84
	v_or_b32_e32 v77, 0x2c00, v84
	v_or_b32_e32 v78, 0x3000, v84
	s_waitcnt lgkmcnt(0)
	v_mfma_f32_32x32x16_bf16 v[32:47], v[232:235], v[64:67], v[32:47]
	global_load_dwordx4 v[124:127], v84, s[92:93]
	global_load_dwordx4 v[120:123], v85, s[92:93]
	global_load_dwordx4 v[116:119], v68, s[92:93]
	global_load_dwordx4 v[112:115], v69, s[92:93]
	global_load_dwordx4 v[108:111], v70, s[92:93]
	global_load_dwordx4 v[104:107], v71, s[92:93]
	global_load_dwordx4 v[100:103], v72, s[92:93]
	global_load_dwordx4 v[96:99], v73, s[92:93]
	global_load_dwordx4 v[92:95], v74, s[92:93]
	global_load_dwordx4 v[88:91], v75, s[92:93]
	global_load_dwordx4 v[84:87], v76, s[92:93]
	global_load_dwordx4 v[80:83], v77, s[92:93]
	s_nop 0
	global_load_dwordx4 v[76:79], v78, s[92:93]
	s_nop 0
	global_load_dwordx4 v[72:75], v185, s[92:93]
	global_load_dwordx4 v[68:71], v186, s[92:93]
	global_load_dwordx4 v[64:67], v187, s[92:93]
	v_mbcnt_lo_u32_b32 v211, -1, 0
	v_mbcnt_hi_u32_b32 v211, -1, v211
	v_readlane_b32 s100, v255, 12
	v_and_b32_e32 v240, 31, v211
	v_lshrrev_b32_e32 v241, 5, v211
	v_lshrrev_b32_e32 v242, 3, v211
	v_and_b32_e32 v243, 7, v211
	v_mov_b32_e32 v245, s100
	v_mul_u32_u24_e32 v245, 0x44, v245
	v_add_u32_e32 v245, 0x1a000, v245
	v_mul_u32_u24_e32 v204, 0x88, v240
	v_lshl_add_u32 v204, v241, 3, v204
	v_add_u32_e32 v204, v245, v204
	v_mul_u32_u24_e32 v205, 0x88, v242
	v_lshl_add_u32 v205, v243, 4, v205
	v_add_u32_e32 v205, v245, v205
	v_sub_u32_e32 v244, v242, v240
	v_lshlrev_b32_e32 v244, 12, v244
	v_lshl_add_u32 v244, v243, 4, v244
	v_lshlrev_b32_e32 v241, 3, v241
	v_sub_u32_e32 v244, v244, v241
	v_add_u32_e32 v207, v175, v244
	v_add_u32_e32 v208, 0x8000, v207
	v_add_u32_e32 v209, 0x10000, v207
	v_add_u32_e32 v210, 0x18000, v207
	v_fma_f32 v48, v174, v48, 0
	v_fma_f32 v49, v174, v49, 0
	v_fma_f32 v50, v174, v50, 0
	v_fma_f32 v51, v174, v51, 0
	v_fma_f32 v52, v174, v52, 0
	v_fma_f32 v53, v174, v53, 0
	v_fma_f32 v54, v174, v54, 0
	v_fma_f32 v55, v174, v55, 0
	v_fma_f32 v56, v174, v56, 0
	v_fma_f32 v57, v174, v57, 0
	v_fma_f32 v58, v174, v58, 0
	v_fma_f32 v59, v174, v59, 0
	v_fma_f32 v60, v174, v60, 0
	v_fma_f32 v61, v174, v61, 0
	v_fma_f32 v62, v174, v62, 0
	v_fma_f32 v63, v174, v63, 0
	v_fma_f32 v32, v174, v32, 0
	v_fma_f32 v33, v174, v33, 0
	v_fma_f32 v34, v174, v34, 0
	v_fma_f32 v35, v174, v35, 0
	v_fma_f32 v36, v174, v36, 0
	v_fma_f32 v37, v174, v37, 0
	v_fma_f32 v38, v174, v38, 0
	v_fma_f32 v39, v174, v39, 0
	v_fma_f32 v40, v174, v40, 0
	v_fma_f32 v41, v174, v41, 0
	v_fma_f32 v42, v174, v42, 0
	v_fma_f32 v43, v174, v43, 0
	v_fma_f32 v44, v174, v44, 0
	v_fma_f32 v45, v174, v45, 0
	v_fma_f32 v46, v174, v46, 0
	v_fma_f32 v47, v174, v47, 0
	v_cvt_pk_bf16_f32 v232, v48, v49
	v_cvt_pk_bf16_f32 v233, v50, v51
	v_cvt_pk_bf16_f32 v234, v52, v53
	v_cvt_pk_bf16_f32 v235, v54, v55
	v_cvt_pk_bf16_f32 v236, v56, v57
	v_cvt_pk_bf16_f32 v237, v58, v59
	v_cvt_pk_bf16_f32 v238, v60, v61
	v_cvt_pk_bf16_f32 v239, v62, v63
	v_cvt_pk_bf16_f32 v240, v32, v33
	v_cvt_pk_bf16_f32 v241, v34, v35
	v_cvt_pk_bf16_f32 v242, v36, v37
	v_cvt_pk_bf16_f32 v243, v38, v39
	v_cvt_pk_bf16_f32 v244, v40, v41
	v_cvt_pk_bf16_f32 v245, v42, v43
	v_cvt_pk_bf16_f32 v246, v44, v45
	v_cvt_pk_bf16_f32 v247, v46, v47
	ds_write_b64 v204, v[232:233]
	ds_write_b64 v204, v[234:235] offset:16
	ds_write_b64 v204, v[236:237] offset:32
	ds_write_b64 v204, v[238:239] offset:48
	ds_write_b64 v204, v[240:241] offset:64
	ds_write_b64 v204, v[242:243] offset:80
	ds_write_b64 v204, v[244:245] offset:96
	ds_write_b64 v204, v[246:247] offset:112
	s_waitcnt lgkmcnt(0)
	ds_read_b128 v[232:235], v205
	ds_read_b128 v[236:239], v205 offset:1088
	ds_read_b128 v[240:243], v205 offset:2176
	ds_read_b128 v[244:247], v205 offset:3264
	s_waitcnt lgkmcnt(0)
	global_store_dwordx4 v207, v[232:235], s[10:11]
	global_store_dwordx4 v208, v[236:239], s[10:11]
	global_store_dwordx4 v209, v[240:243], s[10:11]
	global_store_dwordx4 v210, v[244:247], s[10:11]
	s_nop 1
	ds_read_b128 v[228:231], v169
	ds_read_b128 v[232:235], v169 offset:8192
	ds_read_b128 v[236:239], v169 offset:1024
	ds_read_b128 v[240:243], v169 offset:9216
	ds_read_b128 v[244:247], v169 offset:2048
	ds_read_b128 v[248:251], v169 offset:10240
	s_waitcnt vmcnt(29)
	s_waitcnt lgkmcnt(5)
	v_mfma_f32_32x32x16_bf16 v[16:31], v[228:231], v[164:167], v[16:31]
	ds_read_b128 v[228:231], v169 offset:3072
	s_waitcnt vmcnt(21)
	v_lshlrev_b32_e32 v46, 16, v152
	v_and_b32_e32 v47, 0xffff0000, v152
	v_lshlrev_b32_e32 v48, 16, v153
	v_and_b32_e32 v49, 0xffff0000, v153
	v_lshlrev_b32_e32 v50, 16, v154
	v_and_b32_e32 v51, 0xffff0000, v154
	s_waitcnt lgkmcnt(5)
	v_mfma_f32_32x32x16_bf16 v[0:15], v[232:235], v[164:167], v[0:15]
	ds_read_b128 v[232:235], v169 offset:11264
	v_lshlrev_b32_e32 v52, 16, v155
	v_and_b32_e32 v53, 0xffff0000, v155
	s_waitcnt vmcnt(20)
	v_lshlrev_b32_e32 v54, 16, v149
	v_and_b32_e32 v55, 0xffff0000, v149
	v_lshlrev_b32_e32 v56, 16, v150
	v_and_b32_e32 v57, 0xffff0000, v150
	v_lshlrev_b32_e32 v58, 16, v151
	s_waitcnt lgkmcnt(5)
; #define LAS __attribute__((address_space(3)))
; DI unsigned cvt_pk_bf16(float lo, float hi) { unsigned r; asm volatile("v_cvt_pk_bf16_f32 %0, %1, %2" : "=v"(r) : "v"(lo), "v"(hi)); return r; }
; #define MFMA32(a, b, c) __builtin_amdgcn_mfma_f32_32x32x16_bf16((a), (b), (c), 0, 0, 0)
; template <bool XW, int PASS, bool RMW> ...
;     ...
;       for (int sb = 0; sb < 2; ++sb) {
;         bf16x8 a0[4], a1[4];
; #pragma unroll
;         for (int k = 0; k < 4; ++k) { a0[k] = *(const LAS bf16x8*)(vimg + (cc & 1) * 16384 + (4 * sb + k) * 1024 + lane * 16); a1[k] = *(const LAS bf16x8*)(vimg + (cc & 1) * 16384 + 8192 + (4 * sb + k) * 1024 + lane * 16); }
; #pragma unroll
;         for (int k = 0; k < 4; ++k) { st0 = MFMA32(a0[k], kb0[4 * sb + k], st0); st1 = MFMA32(a1[k], kb0[4 * sb + k], st1); }
;         asm volatile("" : "+v"(st0), "+v"(st1) :: "memory");
; #pragma unroll
;         for (int k = 0; k < 4; ++k) kb0[4 * sb + k] = ldg16(kT, kboff0 + (unsigned)cn * 262144u + 1024u * (4 * sb + k));
;       }
; #pragma unroll
;       for (int t = 0; t < 2; ++t) {
;         const int sv = 2 * dq + t;
;         *(LAS bf16x8*)(vimg + ((cc + 1) & 1) * 16384 + et * 8192 + sv * 1024 + lane * 16) = scale_tab(vr[t], kdec + 16 * sv + 8 * h);
;         vr[t] = ldg16(vT, vaoff0 + (unsigned)cnn * 524288u + 1024u * sv);
;       }
;       LAS bf16_t* sw = Sb + (pbuf ^ 1) * SBE + (4 * h) * 264 + 32 * w + r;
; #pragma unroll
;       for (int i = 0; i < 16; ++i) {
;         const int eo = ((i & 3) + 8 * (i >> 2)) * 264;
;         const unsigned pkw = cvt_pk_bf16(st0[i], st1[i]);
;         sw[eo] = (bf16_t)(pkw & 0xffffu);
;         sw[eo + 32 * 264] = (bf16_t)(pkw >> 16);
;       }
;       lds_barrier();
;       pbuf ^= 1;
;     }
	v_mfma_f32_32x32x16_bf16 v[16:31], v[236:239], v[160:163], v[16:31]
	ds_read_b128 v[236:239], v169 offset:4096
	v_and_b32_e32 v59, 0xffff0000, v151
	s_waitcnt lgkmcnt(5)
	v_mfma_f32_32x32x16_bf16 v[0:15], v[240:243], v[160:163], v[0:15]
	ds_read_b128 v[240:243], v169 offset:12288
	s_waitcnt lgkmcnt(5)
	v_mfma_f32_32x32x16_bf16 v[16:31], v[244:247], v[156:159], v[16:31]
	ds_read_b128 v[244:247], v169 offset:5120
	s_waitcnt lgkmcnt(5)
	v_mfma_f32_32x32x16_bf16 v[0:15], v[248:251], v[156:159], v[0:15]
	ds_read_b128 v[248:251], v169 offset:13312
	v_lshlrev_b32_e32 v44, 16, v148
	v_and_b32_e32 v45, 0xffff0000, v148
	v_add_u32_e32 v175, 0xfff80000, v175
	s_waitcnt lgkmcnt(5)
	v_mfma_f32_32x32x16_bf16 v[16:31], v[228:231], v[140:143], v[16:31]
	ds_read_b128 v[228:231], v169 offset:6144
	s_waitcnt lgkmcnt(5)
	v_mfma_f32_32x32x16_bf16 v[0:15], v[232:235], v[140:143], v[0:15]
	ds_read_b128 v[232:235], v169 offset:14336
	s_waitcnt lgkmcnt(5)
	v_mfma_f32_32x32x16_bf16 v[16:31], v[236:239], v[144:147], v[16:31]
	ds_read_b128 v[236:239], v169 offset:7168
	s_waitcnt lgkmcnt(5)
	v_mfma_f32_32x32x16_bf16 v[0:15], v[240:243], v[144:147], v[0:15]
	ds_read_b128 v[240:243], v169 offset:15360
	v_mov_b32_e32 v32, s8
	v_sub_u32_e64 v32, s5, v32 clamp
	v_lshl_add_u32 v61, v32, 19, v224
	s_and_b32 s8, s1, 0x4000
	v_add_u32_e32 v60, s8, v198
	v_add_u32_e32 v62, s3, v60
	v_or_b32_e32 v63, s3, v61
	s_waitcnt lgkmcnt(5)
	v_mfma_f32_32x32x16_bf16 v[16:31], v[244:247], v[136:139], v[16:31]
	v_or_b32_e32 v61, s33, v61
	s_mul_i32 s8, s0, 0x8400
	s_cmp_eq_u32 s4, s2
	s_waitcnt lgkmcnt(4)
	v_mfma_f32_32x32x16_bf16 v[0:15], v[248:251], v[136:139], v[0:15]
	s_waitcnt lgkmcnt(3)
	v_mfma_f32_32x32x16_bf16 v[16:31], v[228:231], v[132:135], v[16:31]
	s_waitcnt lgkmcnt(2)
	v_mfma_f32_32x32x16_bf16 v[0:15], v[232:235], v[132:135], v[0:15]
	v_add_u32_e32 v32, v184, v223
	v_or_b32_e32 v33, 0x400, v32
	v_or_b32_e32 v34, 0x800, v32
	v_or_b32_e32 v35, 0xc00, v32
	global_load_dwordx4 v[164:167], v32, s[14:15]
	global_load_dwordx4 v[160:163], v33, s[14:15]
	global_load_dwordx4 v[156:159], v34, s[14:15]
	global_load_dwordx4 v[140:143], v35, s[14:15]
	v_or_b32_e32 v132, 0x1000, v32
	s_waitcnt lgkmcnt(1)
	v_mfma_f32_32x32x16_bf16 v[16:31], v[236:239], v[128:131], v[16:31]
	v_or_b32_e32 v36, 0x1400, v32
	v_or_b32_e32 v37, 0x1800, v32
	v_or_b32_e32 v38, 0x1c00, v32
	s_waitcnt lgkmcnt(0)
	v_mfma_f32_32x32x16_bf16 v[0:15], v[240:243], v[128:131], v[0:15]
	ds_read_b128 v[32:35], v172
	global_load_dwordx4 v[144:147], v132, s[14:15]
	global_load_dwordx4 v[136:139], v36, s[14:15]
	s_nop 0
	global_load_dwordx4 v[132:135], v37, s[14:15]
	global_load_dwordx4 v[128:131], v38, s[14:15]
	ds_read_b128 v[36:39], v172 offset:16
	s_waitcnt lgkmcnt(1)
	v_mul_f32_e32 v32, v32, v46
	v_mul_f32_e32 v33, v33, v47
	v_mul_f32_e32 v34, v34, v48
	v_mul_f32_e32 v35, v35, v49
	s_waitcnt lgkmcnt(0)
	v_mul_f32_e32 v36, v36, v50
	v_mul_f32_e32 v37, v37, v51
	v_mul_f32_e32 v38, v38, v52
	v_mul_f32_e32 v39, v39, v53
	v_cvt_pk_bf16_f32 v32, v32, v33
	v_cvt_pk_bf16_f32 v33, v34, v35
	v_cvt_pk_bf16_f32 v34, v36, v37
	v_cvt_pk_bf16_f32 v35, v38, v39
	ds_write_b128 v62, v[32:35]
	global_load_dwordx4 v[152:155], v63, s[16:17]
	ds_read_b128 v[32:35], v173
	ds_read_b128 v[36:39], v173 offset:16
	s_waitcnt lgkmcnt(1)
	v_mul_f32_e32 v32, v32, v44
	v_mul_f32_e32 v33, v33, v45
	v_mul_f32_e32 v34, v34, v54
	v_mul_f32_e32 v35, v35, v55
	s_waitcnt lgkmcnt(0)
	v_mul_f32_e32 v36, v36, v56
	v_mul_f32_e32 v37, v37, v57
	v_mul_f32_e32 v38, v38, v58
	v_mul_f32_e32 v39, v39, v59
	v_cvt_pk_bf16_f32 v32, v32, v33
	v_cvt_pk_bf16_f32 v33, v34, v35
	v_cvt_pk_bf16_f32 v34, v36, v37
	v_cvt_pk_bf16_f32 v35, v38, v39
	global_load_dwordx4 v[148:151], v61, s[16:17]
	v_add_u32_e32 v37, s33, v60
	v_add_u32_e32 v36, s8, v199
	ds_write_b128 v37, v[32:35]
	v_mbcnt_lo_u32_b32 v251, -1, 0
	v_mbcnt_hi_u32_b32 v251, -1, v251
	v_and_b32_e32 v251, 1, v251
	v_sub_u32_e32 v250, 0, v251
	v_and_b32_e32 v248, 0x06060606, v250
	v_xor_b32_e32 v248, 0x05040100, v248
	v_and_b32_e32 v251, 0x107e, v250
	v_add_u32_e32 v249, v36, v251
	v_cvt_pk_bf16_f32 v232, v16, v20
	v_cvt_pk_bf16_f32 v233, v17, v21
	v_cvt_pk_bf16_f32 v234, v18, v22
	v_cvt_pk_bf16_f32 v235, v19, v23
	v_cvt_pk_bf16_f32 v236, v24, v28
	v_cvt_pk_bf16_f32 v237, v25, v29
	v_cvt_pk_bf16_f32 v238, v26, v30
	v_cvt_pk_bf16_f32 v239, v27, v31
	v_mov_b32_dpp v240, v232 quad_perm:[1,0,3,2] row_mask:0xf bank_mask:0xf
	v_mov_b32_dpp v241, v233 quad_perm:[1,0,3,2] row_mask:0xf bank_mask:0xf
	v_mov_b32_dpp v242, v234 quad_perm:[1,0,3,2] row_mask:0xf bank_mask:0xf
	v_mov_b32_dpp v243, v235 quad_perm:[1,0,3,2] row_mask:0xf bank_mask:0xf
	v_mov_b32_dpp v244, v236 quad_perm:[1,0,3,2] row_mask:0xf bank_mask:0xf
	v_mov_b32_dpp v245, v237 quad_perm:[1,0,3,2] row_mask:0xf bank_mask:0xf
	v_mov_b32_dpp v246, v238 quad_perm:[1,0,3,2] row_mask:0xf bank_mask:0xf
	v_mov_b32_dpp v247, v239 quad_perm:[1,0,3,2] row_mask:0xf bank_mask:0xf
	v_perm_b32 v240, v240, v232, v248
	v_perm_b32 v241, v241, v233, v248
	v_perm_b32 v242, v242, v234, v248
	v_perm_b32 v243, v243, v235, v248
	v_perm_b32 v244, v244, v236, v248
	v_perm_b32 v245, v245, v237, v248
	v_perm_b32 v246, v246, v238, v248
	v_perm_b32 v247, v247, v239, v248
	ds_write_b32 v249, v240 offset:0
	ds_write_b32 v249, v241 offset:528
	ds_write_b32 v249, v242 offset:1056
	ds_write_b32 v249, v243 offset:1584
	ds_write_b32 v249, v244 offset:8448
	ds_write_b32 v249, v245 offset:8976
	ds_write_b32 v249, v246 offset:9504
	ds_write_b32 v249, v247 offset:10032
	v_cvt_pk_bf16_f32 v232, v0, v4
	v_cvt_pk_bf16_f32 v233, v1, v5
	v_cvt_pk_bf16_f32 v234, v2, v6
	v_cvt_pk_bf16_f32 v235, v3, v7
	v_cvt_pk_bf16_f32 v236, v8, v12
	v_cvt_pk_bf16_f32 v237, v9, v13
	v_cvt_pk_bf16_f32 v238, v10, v14
	v_cvt_pk_bf16_f32 v239, v11, v15
	v_mov_b32_dpp v240, v232 quad_perm:[1,0,3,2] row_mask:0xf bank_mask:0xf
	v_mov_b32_dpp v241, v233 quad_perm:[1,0,3,2] row_mask:0xf bank_mask:0xf
	v_mov_b32_dpp v242, v234 quad_perm:[1,0,3,2] row_mask:0xf bank_mask:0xf
	v_mov_b32_dpp v243, v235 quad_perm:[1,0,3,2] row_mask:0xf bank_mask:0xf
	v_mov_b32_dpp v244, v236 quad_perm:[1,0,3,2] row_mask:0xf bank_mask:0xf
	v_mov_b32_dpp v245, v237 quad_perm:[1,0,3,2] row_mask:0xf bank_mask:0xf
	v_mov_b32_dpp v246, v238 quad_perm:[1,0,3,2] row_mask:0xf bank_mask:0xf
	v_mov_b32_dpp v247, v239 quad_perm:[1,0,3,2] row_mask:0xf bank_mask:0xf
	v_perm_b32 v240, v240, v232, v248
	v_perm_b32 v241, v241, v233, v248
	v_perm_b32 v242, v242, v234, v248
	v_perm_b32 v243, v243, v235, v248
	v_perm_b32 v244, v244, v236, v248
	v_perm_b32 v245, v245, v237, v248
	v_perm_b32 v246, v246, v238, v248
	v_perm_b32 v247, v247, v239, v248
	ds_write_b32 v249, v240 offset:16896
	ds_write_b32 v249, v241 offset:17424
	ds_write_b32 v249, v242 offset:17952
	ds_write_b32 v249, v243 offset:18480
	ds_write_b32 v249, v244 offset:25344
	ds_write_b32 v249, v245 offset:25872
	ds_write_b32 v249, v246 offset:26400
	ds_write_b32 v249, v247 offset:26928
	s_waitcnt lgkmcnt(0)
	s_barrier
	s_mov_b32 s8, s2
	s_cbranch_scc0 .LBB0_108
	s_branch .LBB0_68
